# bf16 residual-stream stores of the out-proj / MLP-out epilogue made write-through (sc1) so the out-proj->MLP-in flush has little to write back
# baseline (speedup 1.0000x reference)
; __device__ __forceinline__ unsigned cvt_pk_bf16(float lo, float hi) { f32x2 v = {lo, hi}; bf16x2_t b = __builtin_convertvector(v, bf16x2_t); return __builtin_bit_cast(unsigned, b); }
;     __device__ __forceinline__ void operator()(const f32x4 (&acc)[2][2][4][2], const Unit& u, int wr, int wc, int fr, int fq) const {
;     ...
;                     for (int bj = 0; bj < 2; ++bj) {
;                         const size_t off = (size_t)row * ldc + u.pn * BM + bj * HALF + wc * 32 + 8 * fq;
;                         const u32x4 b = bj == 0 ? bw0 : bw1;
;                         f32x4 b0, b1;
;                         b0[0] = __uint_as_float(b.x << 16); b0[1] = __uint_as_float(b.x & 0xffff0000u); b0[2] = __uint_as_float(b.y << 16); b0[3] = __uint_as_float(b.y & 0xffff0000u);
;                         b1[0] = __uint_as_float(b.z << 16); b1[1] = __uint_as_float(b.z & 0xffff0000u); b1[2] = __uint_as_float(b.w << 16); b1[3] = __uint_as_float(b.w & 0xffff0000u);
;                         const f32x4 v0 = b0 + acc[ai][bj][m][0] * sc, v1 = b1 + acc[ai][bj][m][1] * sc;
;                         if (out != nullptr) { *(f32x4*)(out + off) = v0; *(f32x4*)(out + off + 4) = v1; }
;                         part += (v0[0] * v0[0] + v0[1] * v0[1]) + (v0[2] * v0[2] + v0[3] * v0[3]) + (v1[0] * v1[0] + v1[1] * v1[1]) + (v1[2] * v1[2] + v1[3] * v1[3]);
;                         if (ssq_o1 != nullptr) {
;                             u32x4 w; w.x = cvt_pk_bf16(v0[0], v0[1]); w.y = cvt_pk_bf16(v0[2], v0[3]); w.z = cvt_pk_bf16(v1[0], v1[1]); w.w = cvt_pk_bf16(v1[2], v1[3]);
;                             *(u32x4*)(O + off) = w;
;                         }
.LBB0_901:
	v_cndmask_b32_e64 v158, 0, 1, s[74:75]
	v_cmp_ne_u32_e64 s[46:47], 1, v158
	s_andn2_b64 vcc, exec, s[74:75]
	s_cbranch_vccnz .LBB0_903
	v_cvt_pk_bf16_f32 v216, v124, v125
	v_cvt_pk_bf16_f32 v217, v126, v127
	v_cvt_pk_bf16_f32 v218, v120, v121
	v_cvt_pk_bf16_f32 v219, v122, v123
	v_lshl_add_u64 v[158:159], v[200:201], 1, s[68:69]
	global_store_dwordx4 v[158:159], v[216:219], off sc1

; __device__ __forceinline__ unsigned cvt_pk_bf16(float lo, float hi) { f32x2 v = {lo, hi}; bf16x2_t b = __builtin_convertvector(v, bf16x2_t); return __builtin_bit_cast(unsigned, b); }
;     __device__ __forceinline__ void operator()(const f32x4 (&acc)[2][2][4][2], const Unit& u, int wr, int wc, int fr, int fq) const {
;     ...
;                         if (ssq_o1 != nullptr) {
;                             u32x4 w; w.x = cvt_pk_bf16(v0[0], v0[1]); w.y = cvt_pk_bf16(v0[2], v0[3]); w.z = cvt_pk_bf16(v1[0], v1[1]); w.w = cvt_pk_bf16(v1[2], v1[3]);
;                             *(u32x4*)(O + off) = w;
;                         }
.LBB0_905:
	v_or_b32_e32 v152, 0x80, v174
	s_and_b64 vcc, exec, s[46:47]
	v_mov_b32_e32 v153, v175
	s_cbranch_vccnz .LBB0_907
	v_lshl_add_u64 v[158:159], v[196:197], 0, v[152:153]
	v_cvt_pk_bf16_f32 v154, v116, v117
	v_cvt_pk_bf16_f32 v155, v118, v119
	v_cvt_pk_bf16_f32 v156, v112, v113
	v_cvt_pk_bf16_f32 v157, v114, v115
	v_lshl_add_u64 v[158:159], v[158:159], 1, s[68:69]
	global_store_dwordx4 v[158:159], v[154:157], off sc1

; __device__ __forceinline__ unsigned cvt_pk_bf16(float lo, float hi) { f32x2 v = {lo, hi}; bf16x2_t b = __builtin_convertvector(v, bf16x2_t); return __builtin_bit_cast(unsigned, b); }
;     __device__ __forceinline__ void operator()(const f32x4 (&acc)[2][2][4][2], const Unit& u, int wr, int wc, int fr, int fq) const {
;     ...
;                         if (ssq_o1 != nullptr) {
;                             u32x4 w; w.x = cvt_pk_bf16(v0[0], v0[1]); w.y = cvt_pk_bf16(v0[2], v0[3]); w.z = cvt_pk_bf16(v1[0], v1[1]); w.w = cvt_pk_bf16(v1[2], v1[3]);
;                             *(u32x4*)(O + off) = w;
;                         }
.LBB0_913:
	s_and_b64 vcc, exec, s[46:47]
	s_cbranch_vccnz .LBB0_915
	v_cvt_pk_bf16_f32 v120, v108, v109
	v_cvt_pk_bf16_f32 v121, v110, v111
	v_cvt_pk_bf16_f32 v122, v104, v105
	v_cvt_pk_bf16_f32 v123, v106, v107
	v_lshl_add_u64 v[116:117], v[116:117], 1, s[68:69]
	global_store_dwordx4 v[116:117], v[120:123], off sc1

; __device__ __forceinline__ unsigned cvt_pk_bf16(float lo, float hi) { f32x2 v = {lo, hi}; bf16x2_t b = __builtin_convertvector(v, bf16x2_t); return __builtin_bit_cast(unsigned, b); }
;     __device__ __forceinline__ void operator()(const f32x4 (&acc)[2][2][4][2], const Unit& u, int wr, int wc, int fr, int fq) const {
;     ...
;                         if (ssq_o1 != nullptr) {
;                             u32x4 w; w.x = cvt_pk_bf16(v0[0], v0[1]); w.y = cvt_pk_bf16(v0[2], v0[3]); w.z = cvt_pk_bf16(v1[0], v1[1]); w.w = cvt_pk_bf16(v1[2], v1[3]);
;                             *(u32x4*)(O + off) = w;
;                         }
.LBB0_917:
	s_and_b64 vcc, exec, s[46:47]
	s_cbranch_vccnz .LBB0_919
	v_lshl_add_u64 v[116:117], v[194:195], 0, v[152:153]
	v_cvt_pk_bf16_f32 v112, v100, v101
	v_cvt_pk_bf16_f32 v113, v102, v103
	v_cvt_pk_bf16_f32 v114, v96, v97
	v_cvt_pk_bf16_f32 v115, v98, v99
	v_lshl_add_u64 v[116:117], v[116:117], 1, s[68:69]
	global_store_dwordx4 v[116:117], v[112:115], off sc1

; __device__ __forceinline__ unsigned cvt_pk_bf16(float lo, float hi) { f32x2 v = {lo, hi}; bf16x2_t b = __builtin_convertvector(v, bf16x2_t); return __builtin_bit_cast(unsigned, b); }
;     __device__ __forceinline__ void operator()(const f32x4 (&acc)[2][2][4][2], const Unit& u, int wr, int wc, int fr, int fq) const {
;     ...
;                         if (ssq_o1 != nullptr) {
;                             u32x4 w; w.x = cvt_pk_bf16(v0[0], v0[1]); w.y = cvt_pk_bf16(v0[2], v0[3]); w.z = cvt_pk_bf16(v1[0], v1[1]); w.w = cvt_pk_bf16(v1[2], v1[3]);
;                             *(u32x4*)(O + off) = w;
;                         }
.LBB0_925:
	s_and_b64 vcc, exec, s[46:47]
	s_cbranch_vccnz .LBB0_927
	v_cvt_pk_bf16_f32 v102, v92, v93
	v_cvt_pk_bf16_f32 v103, v94, v95
	v_cvt_pk_bf16_f32 v104, v88, v89
	v_cvt_pk_bf16_f32 v105, v90, v91
	v_lshl_add_u64 v[100:101], v[100:101], 1, s[68:69]
	global_store_dwordx4 v[100:101], v[102:105], off sc1

; __device__ __forceinline__ unsigned cvt_pk_bf16(float lo, float hi) { f32x2 v = {lo, hi}; bf16x2_t b = __builtin_convertvector(v, bf16x2_t); return __builtin_bit_cast(unsigned, b); }
;     __device__ __forceinline__ void operator()(const f32x4 (&acc)[2][2][4][2], const Unit& u, int wr, int wc, int fr, int fq) const {
;     ...
;                         if (ssq_o1 != nullptr) {
;                             u32x4 w; w.x = cvt_pk_bf16(v0[0], v0[1]); w.y = cvt_pk_bf16(v0[2], v0[3]); w.z = cvt_pk_bf16(v1[0], v1[1]); w.w = cvt_pk_bf16(v1[2], v1[3]);
;                             *(u32x4*)(O + off) = w;
;                         }
.LBB0_929:
	s_and_b64 vcc, exec, s[46:47]
	s_cbranch_vccnz .LBB0_931
	v_lshl_add_u64 v[100:101], v[190:191], 0, v[152:153]
	v_cvt_pk_bf16_f32 v96, v84, v85
	v_cvt_pk_bf16_f32 v97, v86, v87
	v_cvt_pk_bf16_f32 v98, v80, v81
	v_cvt_pk_bf16_f32 v99, v82, v83
	v_lshl_add_u64 v[100:101], v[100:101], 1, s[68:69]
	global_store_dwordx4 v[100:101], v[96:99], off sc1

; __device__ __forceinline__ unsigned cvt_pk_bf16(float lo, float hi) { f32x2 v = {lo, hi}; bf16x2_t b = __builtin_convertvector(v, bf16x2_t); return __builtin_bit_cast(unsigned, b); }
;     __device__ __forceinline__ void operator()(const f32x4 (&acc)[2][2][4][2], const Unit& u, int wr, int wc, int fr, int fq) const {
;     ...
;                         if (ssq_o1 != nullptr) {
;                             u32x4 w; w.x = cvt_pk_bf16(v0[0], v0[1]); w.y = cvt_pk_bf16(v0[2], v0[3]); w.z = cvt_pk_bf16(v1[0], v1[1]); w.w = cvt_pk_bf16(v1[2], v1[3]);
;                             *(u32x4*)(O + off) = w;
;                         }
.LBB0_937:
	s_and_b64 vcc, exec, s[46:47]
	s_cbranch_vccnz .LBB0_939
	v_cvt_pk_bf16_f32 v86, v76, v77
	v_cvt_pk_bf16_f32 v87, v78, v79
	v_cvt_pk_bf16_f32 v88, v72, v73
	v_cvt_pk_bf16_f32 v89, v74, v75
	v_lshl_add_u64 v[84:85], v[84:85], 1, s[68:69]
	global_store_dwordx4 v[84:85], v[86:89], off sc1

; __device__ __forceinline__ unsigned cvt_pk_bf16(float lo, float hi) { f32x2 v = {lo, hi}; bf16x2_t b = __builtin_convertvector(v, bf16x2_t); return __builtin_bit_cast(unsigned, b); }
;     __device__ __forceinline__ void operator()(const f32x4 (&acc)[2][2][4][2], const Unit& u, int wr, int wc, int fr, int fq) const {
;     ...
;                         if (ssq_o1 != nullptr) {
;                             u32x4 w; w.x = cvt_pk_bf16(v0[0], v0[1]); w.y = cvt_pk_bf16(v0[2], v0[3]); w.z = cvt_pk_bf16(v1[0], v1[1]); w.w = cvt_pk_bf16(v1[2], v1[3]);
;                             *(u32x4*)(O + off) = w;
;                         }
.LBB0_941:
	s_and_b64 vcc, exec, s[46:47]
	s_cbranch_vccnz .LBB0_943
	v_lshl_add_u64 v[84:85], v[186:187], 0, v[152:153]
	v_cvt_pk_bf16_f32 v80, v68, v69
	v_cvt_pk_bf16_f32 v81, v70, v71
	v_cvt_pk_bf16_f32 v82, v64, v65
	v_cvt_pk_bf16_f32 v83, v66, v67
	v_lshl_add_u64 v[84:85], v[84:85], 1, s[68:69]
	global_store_dwordx4 v[84:85], v[80:83], off sc1

; __device__ __forceinline__ unsigned cvt_pk_bf16(float lo, float hi) { f32x2 v = {lo, hi}; bf16x2_t b = __builtin_convertvector(v, bf16x2_t); return __builtin_bit_cast(unsigned, b); }
;     __device__ __forceinline__ void operator()(const f32x4 (&acc)[2][2][4][2], const Unit& u, int wr, int wc, int fr, int fq) const {
;     ...
;                         if (ssq_o1 != nullptr) {
;                             u32x4 w; w.x = cvt_pk_bf16(v0[0], v0[1]); w.y = cvt_pk_bf16(v0[2], v0[3]); w.z = cvt_pk_bf16(v1[0], v1[1]); w.w = cvt_pk_bf16(v1[2], v1[3]);
;                             *(u32x4*)(O + off) = w;
;                         }
.LBB0_949:
	s_and_b64 vcc, exec, s[46:47]
	s_cbranch_vccnz .LBB0_951
	v_cvt_pk_bf16_f32 v110, v60, v61
	v_cvt_pk_bf16_f32 v111, v62, v63
	v_cvt_pk_bf16_f32 v112, v56, v57
	v_cvt_pk_bf16_f32 v113, v58, v59
	v_lshl_add_u64 v[94:95], v[108:109], 1, s[68:69]
	global_store_dwordx4 v[94:95], v[110:113], off sc1

; __device__ __forceinline__ unsigned cvt_pk_bf16(float lo, float hi) { f32x2 v = {lo, hi}; bf16x2_t b = __builtin_convertvector(v, bf16x2_t); return __builtin_bit_cast(unsigned, b); }
;     __device__ __forceinline__ void operator()(const f32x4 (&acc)[2][2][4][2], const Unit& u, int wr, int wc, int fr, int fq) const {
;     ...
;                         if (ssq_o1 != nullptr) {
;                             u32x4 w; w.x = cvt_pk_bf16(v0[0], v0[1]); w.y = cvt_pk_bf16(v0[2], v0[3]); w.z = cvt_pk_bf16(v1[0], v1[1]); w.w = cvt_pk_bf16(v1[2], v1[3]);
;                             *(u32x4*)(O + off) = w;
;                         }
.LBB0_953:
	s_and_b64 vcc, exec, s[46:47]
	s_cbranch_vccnz .LBB0_955
	v_lshl_add_u64 v[92:93], v[104:105], 0, v[152:153]
	v_cvt_pk_bf16_f32 v88, v52, v53
	v_cvt_pk_bf16_f32 v89, v54, v55
	v_cvt_pk_bf16_f32 v90, v48, v49
	v_cvt_pk_bf16_f32 v91, v50, v51
	v_lshl_add_u64 v[92:93], v[92:93], 1, s[68:69]
	global_store_dwordx4 v[92:93], v[88:91], off sc1

; __device__ __forceinline__ unsigned cvt_pk_bf16(float lo, float hi) { f32x2 v = {lo, hi}; bf16x2_t b = __builtin_convertvector(v, bf16x2_t); return __builtin_bit_cast(unsigned, b); }
;     __device__ __forceinline__ void operator()(const f32x4 (&acc)[2][2][4][2], const Unit& u, int wr, int wc, int fr, int fq) const {
;     ...
;                         if (ssq_o1 != nullptr) {
;                             u32x4 w; w.x = cvt_pk_bf16(v0[0], v0[1]); w.y = cvt_pk_bf16(v0[2], v0[3]); w.z = cvt_pk_bf16(v1[0], v1[1]); w.w = cvt_pk_bf16(v1[2], v1[3]);
;                             *(u32x4*)(O + off) = w;
;                         }
.LBB0_961:
	s_and_b64 vcc, exec, s[46:47]
	s_cbranch_vccnz .LBB0_963
	v_cvt_pk_bf16_f32 v56, v44, v45
	v_cvt_pk_bf16_f32 v57, v46, v47
	v_cvt_pk_bf16_f32 v58, v40, v41
	v_cvt_pk_bf16_f32 v59, v42, v43
	v_lshl_add_u64 v[54:55], v[54:55], 1, s[68:69]
	global_store_dwordx4 v[54:55], v[56:59], off sc1

; __device__ __forceinline__ unsigned cvt_pk_bf16(float lo, float hi) { f32x2 v = {lo, hi}; bf16x2_t b = __builtin_convertvector(v, bf16x2_t); return __builtin_bit_cast(unsigned, b); }
;     __device__ __forceinline__ void operator()(const f32x4 (&acc)[2][2][4][2], const Unit& u, int wr, int wc, int fr, int fq) const {
;     ...
;                         if (ssq_o1 != nullptr) {
;                             u32x4 w; w.x = cvt_pk_bf16(v0[0], v0[1]); w.y = cvt_pk_bf16(v0[2], v0[3]); w.z = cvt_pk_bf16(v1[0], v1[1]); w.w = cvt_pk_bf16(v1[2], v1[3]);
;                             *(u32x4*)(O + off) = w;
;                         }
.LBB0_965:
	s_and_b64 vcc, exec, s[46:47]
	s_cbranch_vccnz .LBB0_967
	v_lshl_add_u64 v[52:53], v[48:49], 0, v[152:153]
	v_cvt_pk_bf16_f32 v48, v36, v37
	v_cvt_pk_bf16_f32 v49, v38, v39
	v_cvt_pk_bf16_f32 v50, v32, v33
	v_cvt_pk_bf16_f32 v51, v34, v35
	v_lshl_add_u64 v[52:53], v[52:53], 1, s[68:69]
	global_store_dwordx4 v[52:53], v[48:51], off sc1

; __device__ __forceinline__ unsigned cvt_pk_bf16(float lo, float hi) { f32x2 v = {lo, hi}; bf16x2_t b = __builtin_convertvector(v, bf16x2_t); return __builtin_bit_cast(unsigned, b); }
;     __device__ __forceinline__ void operator()(const f32x4 (&acc)[2][2][4][2], const Unit& u, int wr, int wc, int fr, int fq) const {
;     ...
;                         if (ssq_o1 != nullptr) {
;                             u32x4 w; w.x = cvt_pk_bf16(v0[0], v0[1]); w.y = cvt_pk_bf16(v0[2], v0[3]); w.z = cvt_pk_bf16(v1[0], v1[1]); w.w = cvt_pk_bf16(v1[2], v1[3]);
;                             *(u32x4*)(O + off) = w;
;                         }
.LBB0_973:
	s_and_b64 vcc, exec, s[46:47]
	s_cbranch_vccnz .LBB0_975
	v_cvt_pk_bf16_f32 v40, v28, v29
	v_cvt_pk_bf16_f32 v41, v30, v31
	v_cvt_pk_bf16_f32 v42, v24, v25
	v_cvt_pk_bf16_f32 v43, v26, v27
	v_lshl_add_u64 v[38:39], v[38:39], 1, s[68:69]
	global_store_dwordx4 v[38:39], v[40:43], off sc1

; __device__ __forceinline__ unsigned cvt_pk_bf16(float lo, float hi) { f32x2 v = {lo, hi}; bf16x2_t b = __builtin_convertvector(v, bf16x2_t); return __builtin_bit_cast(unsigned, b); }
;     __device__ __forceinline__ void operator()(const f32x4 (&acc)[2][2][4][2], const Unit& u, int wr, int wc, int fr, int fq) const {
;     ...
;                         if (ssq_o1 != nullptr) {
;                             u32x4 w; w.x = cvt_pk_bf16(v0[0], v0[1]); w.y = cvt_pk_bf16(v0[2], v0[3]); w.z = cvt_pk_bf16(v1[0], v1[1]); w.w = cvt_pk_bf16(v1[2], v1[3]);
;                             *(u32x4*)(O + off) = w;
;                         }
.LBB0_977:
	s_and_b64 vcc, exec, s[46:47]
	s_cbranch_vccnz .LBB0_979
	v_lshl_add_u64 v[36:37], v[32:33], 0, v[152:153]
	v_cvt_pk_bf16_f32 v32, v20, v21
	v_cvt_pk_bf16_f32 v33, v22, v23
	v_cvt_pk_bf16_f32 v34, v16, v17
	v_cvt_pk_bf16_f32 v35, v18, v19
	v_lshl_add_u64 v[36:37], v[36:37], 1, s[68:69]
	global_store_dwordx4 v[36:37], v[32:35], off sc1

; __device__ __forceinline__ unsigned cvt_pk_bf16(float lo, float hi) { f32x2 v = {lo, hi}; bf16x2_t b = __builtin_convertvector(v, bf16x2_t); return __builtin_bit_cast(unsigned, b); }
;     __device__ __forceinline__ void operator()(const f32x4 (&acc)[2][2][4][2], const Unit& u, int wr, int wc, int fr, int fq) const {
;     ...
;                         if (ssq_o1 != nullptr) {
;                             u32x4 w; w.x = cvt_pk_bf16(v0[0], v0[1]); w.y = cvt_pk_bf16(v0[2], v0[3]); w.z = cvt_pk_bf16(v1[0], v1[1]); w.w = cvt_pk_bf16(v1[2], v1[3]);
;                             *(u32x4*)(O + off) = w;
;                         }
.LBB0_985:
	s_and_b64 vcc, exec, s[46:47]
	s_cbranch_vccnz .LBB0_987
	v_cvt_pk_bf16_f32 v24, v12, v13
	v_cvt_pk_bf16_f32 v25, v14, v15
	v_cvt_pk_bf16_f32 v26, v8, v9
	v_cvt_pk_bf16_f32 v27, v10, v11
	v_lshl_add_u64 v[22:23], v[22:23], 1, s[68:69]
	global_store_dwordx4 v[22:23], v[24:27], off sc1

; __device__ __forceinline__ unsigned cvt_pk_bf16(float lo, float hi) { f32x2 v = {lo, hi}; bf16x2_t b = __builtin_convertvector(v, bf16x2_t); return __builtin_bit_cast(unsigned, b); }
;     __device__ __forceinline__ void operator()(const f32x4 (&acc)[2][2][4][2], const Unit& u, int wr, int wc, int fr, int fq) const {
;     ...
;                         if (ssq_o1 != nullptr) {
;                             u32x4 w; w.x = cvt_pk_bf16(v0[0], v0[1]); w.y = cvt_pk_bf16(v0[2], v0[3]); w.z = cvt_pk_bf16(v1[0], v1[1]); w.w = cvt_pk_bf16(v1[2], v1[3]);
;                             *(u32x4*)(O + off) = w;
;                         }
.LBB0_989:
	s_and_b64 vcc, exec, s[46:47]
	s_cbranch_vccnz .LBB0_991
	v_lshl_add_u64 v[20:21], v[16:17], 0, v[152:153]
	v_cvt_pk_bf16_f32 v16, v4, v5
	v_cvt_pk_bf16_f32 v17, v6, v7
	v_cvt_pk_bf16_f32 v18, v0, v1
	v_cvt_pk_bf16_f32 v19, v2, v3
	v_lshl_add_u64 v[20:21], v[20:21], 1, s[68:69]
	global_store_dwordx4 v[20:21], v[16:19], off sc1
